# grid barrier: the acquire's L1 invalidate is issued when a workgroup arrives (no L1-allocating loads until it resumes) instead of after the release is observed
# speedup vs baseline: 1.0106x; 1.0106x over previous
.LBB0_334:
	s_mov_b64 s[2:3], s[88:89]
	s_getreg_b32 s4, hwreg(HW_REG_XCC_ID, 0, 4)
	s_waitcnt vmcnt(0)
	s_barrier
	s_mov_b64 s[0:1], exec
	v_readlane_b32 s6, v254, 5
	v_readlane_b32 s7, v254, 6
	s_and_b64 s[6:7], s[0:1], s[6:7]
	s_mov_b64 exec, s[6:7]
	s_cbranch_execz .LBB0_386
	s_add_i32 s5, 0, 0x220f0
	v_mov_b32_e32 v0, s5
	buffer_inv sc1
	s_load_dwordx2 s[2:3], s[2:3], 0x170
	s_waitcnt expcnt(0) lgkmcnt(0)
	ds_read_b32 v2, v0
	s_add_i32 s5, 0, 0x220f4
	v_mov_b32_e32 v0, s5
	ds_read_b32 v0, v0
	s_and_b32 s18, s4, 15
	s_waitcnt lgkmcnt(1)
	v_cmp_ne_u32_e32 vcc, 0, v2
	s_cbranch_vccnz .LBB0_350
	v_readlane_b32 s4, v254, 1
	v_readlane_b32 s5, v254, 2
	s_mul_i32 s19, s5, s24
	s_mul_i32 s19, s19, s4
	s_add_u32 s4, s2, 0x1000
	s_addc_u32 s5, s3, 0
	s_add_u32 s6, s2, 0x1100
	s_addc_u32 s7, s3, 0
	s_add_u32 s8, s2, 0x1200
	s_addc_u32 s9, s3, 0
	s_add_u32 s10, s2, 0x1300
	s_addc_u32 s11, s3, 0
	s_mov_b32 s20, 1
	v_mov_b32_e32 v16, 0
	s_branch .LBB0_338

.LBB0_365:
	s_or_b64 exec, exec, s[8:9]
	s_waitcnt vmcnt(0)
	s_waitcnt vmcnt(0)

.LBB0_383:
	s_or_b64 exec, exec, s[2:3]
	s_mov_b64 s[2:3], exec
	v_mbcnt_lo_u32_b32 v0, s2, 0
	v_mbcnt_hi_u32_b32 v0, s3, v0
	v_cmp_eq_u32_e32 vcc, 0, v0
	s_waitcnt vmcnt(0)
	s_and_saveexec_b64 s[6:7], vcc
	s_cbranch_execz .LBB0_385
	s_bcnt1_i32_b64 s2, s[2:3]
	v_mov_b32_e32 v0, 0x2000
	v_mov_b32_e32 v1, s2
	global_atomic_add v0, v1, s[4:5] offset:1024

.Lpre_done:
.LBB0_391:
	s_or_b64 exec, exec, s[0:1]
	s_mov_b64 s[2:3], s[88:89]
	s_getreg_b32 s4, hwreg(HW_REG_XCC_ID, 0, 4)
	s_waitcnt vmcnt(0)
	s_barrier
	s_mov_b64 s[0:1], exec
	v_readlane_b32 s6, v254, 5
	v_readlane_b32 s7, v254, 6
	s_and_b64 s[6:7], s[0:1], s[6:7]
	s_mov_b64 exec, s[6:7]
	s_cbranch_execz .LBB0_443
	s_add_i32 s5, 0, 0x220f0
	v_mov_b32_e32 v0, s5
	buffer_inv sc1
	s_load_dwordx2 s[2:3], s[2:3], 0x170
	s_waitcnt expcnt(0) lgkmcnt(0)
	ds_read_b32 v2, v0
	s_add_i32 s5, 0, 0x220f4
	v_mov_b32_e32 v0, s5
	ds_read_b32 v0, v0
	s_and_b32 s18, s4, 15
	s_waitcnt lgkmcnt(1)
	v_cmp_ne_u32_e32 vcc, 0, v2
	s_cbranch_vccnz .LBB0_407
	v_readlane_b32 s4, v254, 1
	v_readlane_b32 s5, v254, 2
	s_mul_i32 s19, s5, s24
	s_mul_i32 s19, s19, s4
	s_add_u32 s4, s2, 0x1000
	s_addc_u32 s5, s3, 0
	s_add_u32 s6, s2, 0x1100
	s_addc_u32 s7, s3, 0
	s_add_u32 s8, s2, 0x1200
	s_addc_u32 s9, s3, 0
	s_add_u32 s10, s2, 0x1300
	s_addc_u32 s11, s3, 0
	s_mov_b32 s20, 1
	v_mov_b32_e32 v16, 0
	s_branch .LBB0_395

.LBB0_640:
	s_mov_b64 s[0:1], s[88:89]
	s_getreg_b32 s8, hwreg(HW_REG_XCC_ID, 0, 4)
	s_waitcnt vmcnt(0)
	s_waitcnt lgkmcnt(0)
	s_barrier
	s_mov_b64 s[10:11], exec
	v_readlane_b32 s12, v254, 5
	v_readlane_b32 s13, v254, 6
	s_and_b64 s[12:13], s[10:11], s[12:13]
	s_mov_b64 exec, s[12:13]
	s_cbranch_execz .LBB0_450
	buffer_inv sc1
	s_load_dwordx2 s[12:13], s[0:1], 0x170
	v_readlane_b32 s0, v254, 45
	s_waitcnt expcnt(0) lgkmcnt(0)
	s_and_b32 s36, s8, 15
	v_mov_b32_e32 v0, s0
	ds_read_b32 v2, v0
	v_readlane_b32 s0, v254, 46
	s_waitcnt lgkmcnt(0)
	v_cmp_ne_u32_e32 vcc, 0, v2
	v_mov_b32_e32 v0, s0
	ds_read_b32 v0, v0
	s_cbranch_vccnz .LBB0_656
	s_add_u32 s14, s12, 0x1000
	s_addc_u32 s15, s13, 0
	s_add_u32 s20, s12, 0x1100
	s_addc_u32 s21, s13, 0
	s_add_u32 s22, s12, 0x1200
	s_addc_u32 s23, s13, 0
	s_add_u32 s24, s12, 0x1300
	s_addc_u32 s25, s13, 0
	s_mov_b32 s8, 1
	s_branch .LBB0_644

.LBB0_671:
	s_or_b64 exec, exec, s[22:23]
	s_waitcnt vmcnt(0)
	s_waitcnt vmcnt(0)

.LBB0_689:
	s_or_b64 exec, exec, s[8:9]
	s_mov_b64 s[0:1], exec
	v_mbcnt_lo_u32_b32 v0, s0, 0
	v_mbcnt_hi_u32_b32 v0, s1, v0
	v_cmp_eq_u32_e32 vcc, 0, v0
	s_waitcnt vmcnt(0)
	s_and_saveexec_b64 s[8:9], vcc
	s_cbranch_execz .LBB0_449
	s_bcnt1_i32_b64 s0, s[0:1]
	v_mov_b32_e32 v0, s0
	v_mov_b32_e32 v1, 0x2000
	global_atomic_add v1, v0, s[14:15] offset:1024
	s_branch .LBB0_449

.LBB0_949:
	s_mov_b64 s[0:1], s[88:89]
	s_getreg_b32 s8, hwreg(HW_REG_XCC_ID, 0, 4)
	s_waitcnt vmcnt(0)
	s_barrier
	s_mov_b64 s[2:3], exec
	v_readlane_b32 s10, v254, 5
	v_readlane_b32 s11, v254, 6
	s_and_b64 s[10:11], s[2:3], s[10:11]
	s_mov_b64 exec, s[10:11]
	s_cbranch_execz .LBB0_694
	buffer_inv sc1
	s_load_dwordx2 s[10:11], s[0:1], 0x170
	v_readlane_b32 s0, v254, 45
	s_waitcnt expcnt(0) lgkmcnt(0)
	s_and_b32 s16, s8, 15
	v_mov_b32_e32 v0, s0
	ds_read_b32 v2, v0
	v_readlane_b32 s0, v254, 46
	s_waitcnt lgkmcnt(0)
	v_cmp_ne_u32_e32 vcc, 0, v2
	v_mov_b32_e32 v0, s0
	ds_read_b32 v0, v0
	s_cbranch_vccnz .LBB0_965
	s_add_u32 s12, s10, 0x1000
	s_addc_u32 s13, s11, 0
	s_add_u32 s14, s10, 0x1100
	s_addc_u32 s15, s11, 0
	s_add_u32 s20, s10, 0x1200
	s_addc_u32 s21, s11, 0
	s_add_u32 s22, s10, 0x1300
	s_addc_u32 s23, s11, 0
	s_mov_b32 s8, 1
	s_branch .LBB0_953

.LBB0_980:
	s_or_b64 exec, exec, s[20:21]
	s_waitcnt vmcnt(0)
	s_waitcnt vmcnt(0)

.LBB0_998:
	s_or_b64 exec, exec, s[8:9]
	s_mov_b64 s[0:1], exec
	v_mbcnt_lo_u32_b32 v0, s0, 0
	v_mbcnt_hi_u32_b32 v0, s1, v0
	v_cmp_eq_u32_e32 vcc, 0, v0
	s_waitcnt vmcnt(0)
	s_and_saveexec_b64 s[8:9], vcc
	s_cbranch_execz .LBB0_693
	s_bcnt1_i32_b64 s0, s[0:1]
	v_mov_b32_e32 v0, s0
	v_mov_b32_e32 v1, 0x2000
	global_atomic_add v1, v0, s[12:13] offset:1024
	s_branch .LBB0_693

.LBB0_1033:
	s_mov_b64 s[0:1], s[88:89]
	s_getreg_b32 s8, hwreg(HW_REG_XCC_ID, 0, 4)
	s_waitcnt vmcnt(0)
	s_waitcnt vmcnt(63) expcnt(7) lgkmcnt(15)
	s_barrier
	s_mov_b64 s[10:11], exec
	v_readlane_b32 s12, v254, 5
	v_readlane_b32 s13, v254, 6
	s_and_b64 s[12:13], s[10:11], s[12:13]
	s_mov_b64 exec, s[12:13]
	s_cbranch_execz .LBB0_1003
	buffer_inv sc1
	s_load_dwordx2 s[12:13], s[0:1], 0x170
	v_readlane_b32 s0, v254, 45
	s_waitcnt expcnt(0) lgkmcnt(0)
	s_and_b32 s16, s8, 15
	v_mov_b32_e32 v0, s0
	ds_read_b32 v2, v0
	v_readlane_b32 s0, v254, 46
	s_waitcnt lgkmcnt(0)
	v_cmp_ne_u32_e32 vcc, 0, v2
	v_mov_b32_e32 v0, s0
	ds_read_b32 v0, v0
	s_cbranch_vccnz .LBB0_1049
	s_add_u32 s14, s12, 0x1000
	s_addc_u32 s15, s13, 0
	s_add_u32 s20, s12, 0x1100
	s_addc_u32 s21, s13, 0
	s_add_u32 s22, s12, 0x1200
	s_addc_u32 s23, s13, 0
	s_add_u32 s24, s12, 0x1300
	s_addc_u32 s25, s13, 0
	s_mov_b32 s8, 1
	s_branch .LBB0_1037

.LBB0_1107:
	s_mov_b64 s[0:1], s[88:89]
	s_getreg_b32 s8, hwreg(HW_REG_XCC_ID, 0, 4)
	s_waitcnt vmcnt(0)
	s_waitcnt lgkmcnt(0)
	s_barrier
	s_mov_b64 s[2:3], exec
	v_readlane_b32 s10, v254, 5
	v_readlane_b32 s11, v254, 6
	s_and_b64 s[10:11], s[2:3], s[10:11]
	s_mov_b64 exec, s[10:11]
	s_cbranch_execz .LBB0_1159
	buffer_inv sc1
	s_load_dwordx2 s[10:11], s[0:1], 0x170
	v_readlane_b32 s0, v254, 45
	s_waitcnt expcnt(0) lgkmcnt(0)
	s_and_b32 s16, s8, 15
	v_mov_b32_e32 v0, s0
	ds_read_b32 v2, v0
	v_readlane_b32 s0, v254, 46
	s_waitcnt lgkmcnt(0)
	v_cmp_ne_u32_e32 vcc, 0, v2
	v_mov_b32_e32 v0, s0
	ds_read_b32 v0, v0
	s_cbranch_vccnz .LBB0_1123
	s_add_u32 s12, s10, 0x1000
	s_addc_u32 s13, s11, 0
	s_add_u32 s14, s10, 0x1100
	s_addc_u32 s15, s11, 0
	s_add_u32 s20, s10, 0x1200
	s_addc_u32 s21, s11, 0
	s_add_u32 s22, s10, 0x1300
	s_addc_u32 s23, s11, 0
	s_mov_b32 s8, 1
	s_branch .LBB0_1111

.LBB0_1156:
	s_or_b64 exec, exec, s[8:9]
	s_mov_b64 s[0:1], exec
	v_mbcnt_lo_u32_b32 v0, s0, 0
	v_mbcnt_hi_u32_b32 v0, s1, v0
	v_cmp_eq_u32_e32 vcc, 0, v0
	s_waitcnt vmcnt(0)
	s_and_saveexec_b64 s[8:9], vcc
	s_cbranch_execz .LBB0_1158
	s_bcnt1_i32_b64 s0, s[0:1]
	v_mov_b32_e32 v0, s0
	v_mov_b32_e32 v1, 0x2000
	global_atomic_add v1, v0, s[12:13] offset:1024

.LBB0_1226:
	s_mov_b64 s[0:1], s[88:89]
	s_getreg_b32 s8, hwreg(HW_REG_XCC_ID, 0, 4)
	s_waitcnt vmcnt(0)
	s_waitcnt lgkmcnt(0)
	s_barrier
	s_mov_b64 s[10:11], exec
	v_readlane_b32 s22, v254, 5
	v_readlane_b32 s23, v254, 6
	s_and_b64 s[22:23], s[10:11], s[22:23]
	s_mov_b64 exec, s[22:23]
	s_cbranch_execz .LBB0_1162
	buffer_inv sc1
	s_load_dwordx2 s[22:23], s[0:1], 0x170
	v_readlane_b32 s0, v254, 45
	s_waitcnt expcnt(0) lgkmcnt(0)
	s_and_b32 s42, s8, 15
	v_mov_b32_e32 v0, s0
	ds_read_b32 v2, v0
	v_readlane_b32 s0, v254, 46
	s_waitcnt lgkmcnt(0)
	v_cmp_ne_u32_e32 vcc, 0, v2
	v_mov_b32_e32 v0, s0
	ds_read_b32 v0, v0
	s_cbranch_vccnz .LBB0_1242
	s_add_u32 s24, s22, 0x1000
	s_addc_u32 s25, s23, 0
	s_add_u32 s26, s22, 0x1100
	s_addc_u32 s27, s23, 0
	s_add_u32 s34, s22, 0x1200
	s_addc_u32 s35, s23, 0
	s_add_u32 s36, s22, 0x1300
	s_addc_u32 s37, s23, 0
	s_mov_b32 s8, 1
	s_branch .LBB0_1230

.LBB0_1257:
	s_or_b64 exec, exec, s[34:35]
	s_waitcnt vmcnt(0)
	s_waitcnt vmcnt(0)

.LBB0_1275:
	s_or_b64 exec, exec, s[8:9]
	s_mov_b64 s[0:1], exec
	v_mbcnt_lo_u32_b32 v0, s0, 0
	v_mbcnt_hi_u32_b32 v0, s1, v0
	v_cmp_eq_u32_e32 vcc, 0, v0
	s_waitcnt vmcnt(0)
	s_and_saveexec_b64 s[8:9], vcc
	s_cbranch_execz .LBB0_1161
	s_bcnt1_i32_b64 s0, s[0:1]
	v_mov_b32_e32 v0, s0
	v_mov_b32_e32 v1, 0x2000
	global_atomic_add v1, v0, s[24:25] offset:1024
	s_branch .LBB0_1161

.LBB0_1292:
	buffer_inv sc1
	s_load_dwordx2 s[12:13], s[0:1], 0x170
	v_readlane_b32 s0, v254, 45
	s_waitcnt expcnt(0) lgkmcnt(0)
	s_and_b32 s16, s8, 15
	v_mov_b32_e32 v0, s0
	ds_read_b32 v2, v0
	v_readlane_b32 s0, v254, 46
	s_waitcnt lgkmcnt(0)
	v_cmp_ne_u32_e32 vcc, 0, v2
	v_mov_b32_e32 v0, s0
	ds_read_b32 v0, v0
	s_cbranch_vccnz .LBB0_1307
	s_add_u32 s14, s12, 0x1000
	s_addc_u32 s15, s13, 0
	s_add_u32 s20, s12, 0x1100
	s_addc_u32 s21, s13, 0
	s_add_u32 s22, s12, 0x1200
	s_addc_u32 s23, s13, 0
	s_add_u32 s24, s12, 0x1300
	s_addc_u32 s25, s13, 0
	s_mov_b32 s8, 1
	s_branch .LBB0_1295

.LBB0_1340:
	s_or_b64 exec, exec, s[8:9]
	s_mov_b64 s[0:1], exec
	v_mbcnt_lo_u32_b32 v0, s0, 0
	v_mbcnt_hi_u32_b32 v0, s1, v0
	v_cmp_eq_u32_e32 vcc, 0, v0
	s_waitcnt vmcnt(0)
	s_and_saveexec_b64 s[8:9], vcc
	s_cbranch_execnz .LBB0_1341
	s_getpc_b64 s[98:99]
